# phases 2 and 4: half of the workgroups run the projection GEMMs before their attention unit (attention and GEMM traffic interleaved across CUs)
# baseline (speedup 1.0000x reference)
.LBB0_141:
	s_or_b64 exec, exec, s[0:1]
	v_readlane_b32 s0, v254, 2
	v_readlane_b32 s1, v254, 3
	s_max_i32 s75, s0, 1
	s_cmp_ge_i32 s75, s1
	s_waitcnt lgkmcnt(0)
	s_barrier
	s_cbranch_scc1 .LBB0_738
	v_readlane_b32 s2, v254, 0
	s_lshl_b32 s34, s2, 5
	s_and_b32 s1, s2, 7
	s_cmp_eq_u32 s1, 0
	v_readlane_b32 s3, v254, 1
	s_cselect_b64 s[4:5], -1, 0
	s_mul_i32 s0, s3, s2
	v_writelane_b32 v254, s4, 11
	s_ashr_i32 s1, s2, 3
	s_ashr_i32 s62, s2, 31
	v_writelane_b32 v254, s5, 12
	s_mul_i32 s63, s0, s30
	s_add_u32 s0, s42, 0xc3520
	v_writelane_b32 v254, s1, 13
	s_addc_u32 s1, s43, 0
	v_writelane_b32 v254, s0, 14
	s_mov_b32 s79, 0
	v_mov_b32_e32 v0, 0
	s_nop 0
	v_writelane_b32 v255, s79, 40
	v_writelane_b32 v254, s1, 15
	s_add_u32 s0, s42, 0xc3528
	s_addc_u32 s1, s43, 0
	v_writelane_b32 v254, s0, 16
	v_mov_b32_e32 v235, 0x358637bd
	s_mov_b32 s64, 0xf800000
	v_writelane_b32 v254, s1, 17
	s_add_u32 s0, s42, 0xc0200
	s_addc_u32 s1, s43, 0
	v_writelane_b32 v254, s0, 18
	s_cmp_eq_u32 s31, 15
	s_mov_b32 s66, 0xbfb8aa3b
	v_writelane_b32 v254, s1, 19
	s_cselect_b64 s[0:1], -1, 0
	v_writelane_b32 v254, s0, 20
	s_cmp_eq_u32 s31, 14
	s_mov_b32 s67, 0x1fffe0
	v_writelane_b32 v254, s1, 21
	s_cselect_b64 s[0:1], -1, 0
	v_writelane_b32 v254, s0, 22
	s_cmp_eq_u32 s31, 13
	s_movk_i32 s68, 0xb00
	v_writelane_b32 v254, s1, 23
	s_cselect_b64 s[0:1], -1, 0
	v_writelane_b32 v254, s0, 24
	s_cmp_eq_u32 s31, 12
	s_movk_i32 s69, 0x1600
	v_writelane_b32 v254, s1, 25
	s_cselect_b64 s[0:1], -1, 0
	v_writelane_b32 v254, s0, 26
	s_cmp_eq_u32 s31, 11
	s_movk_i32 s73, 0x161
	v_writelane_b32 v254, s1, 27
	s_cselect_b64 s[0:1], -1, 0
	v_writelane_b32 v254, s0, 28
	s_cmp_eq_u32 s31, 10
	v_mov_b32_e32 v234, 1
	v_writelane_b32 v254, s1, 29
	s_cselect_b64 s[0:1], -1, 0
	v_writelane_b32 v254, s0, 30
	s_cmp_eq_u32 s31, 9
	v_mbcnt_hi_u32_b32 v238, -1, v233
	v_writelane_b32 v254, s1, 31
	s_cselect_b64 s[0:1], -1, 0
	v_writelane_b32 v254, s0, 32
	s_cmp_eq_u32 s31, 8
	v_mov_b32_e32 v239, 0xf149f2ca
	v_writelane_b32 v254, s1, 33
	s_cselect_b64 s[0:1], -1, 0
	v_writelane_b32 v254, s0, 34
	s_cmp_eq_u32 s31, 7
	v_mov_b32_e32 v240, 0x3e38aa3b
	v_writelane_b32 v254, s1, 35
	s_cselect_b64 s[0:1], -1, 0
	v_writelane_b32 v254, s0, 36
	s_cmp_eq_u32 s31, 6
	v_mov_b64_e32 v[252:253], 0x200
	v_writelane_b32 v254, s1, 37
	s_cselect_b64 s[0:1], -1, 0
	v_writelane_b32 v254, s0, 38
	s_cmp_eq_u32 s31, 5
	v_mov_b64_e32 v[236:237], 0x1ff
	v_writelane_b32 v254, s1, 39
	s_cselect_b64 s[0:1], -1, 0
	v_writelane_b32 v254, s0, 40
	s_cmp_eq_u32 s31, 4
	v_mov_b32_e32 v241, 0xf78
	v_writelane_b32 v254, s1, 41
	s_cselect_b64 s[0:1], -1, 0
	v_writelane_b32 v254, s0, 42
	s_cmp_eq_u32 s31, 3
	s_mov_b64 s[90:91], 0x80
	v_writelane_b32 v254, s1, 43
	s_cselect_b64 s[0:1], -1, 0
	v_writelane_b32 v254, s0, 44
	s_cmp_eq_u32 s31, 2
	s_nop 0
	v_writelane_b32 v254, s1, 45
	s_cselect_b64 s[0:1], -1, 0
	v_writelane_b32 v254, s0, 46
	s_cmp_eq_u32 s31, 1
	s_nop 0
	v_writelane_b32 v254, s1, 47
	s_cselect_b64 s[0:1], -1, 0
	v_writelane_b32 v254, s0, 48
	s_cmp_eq_u32 s31, 0
	s_nop 0
	v_writelane_b32 v254, s1, 49
	s_cselect_b64 s[0:1], -1, 0
	v_writelane_b32 v254, s0, 50
	s_nop 1
	v_writelane_b32 v254, s1, 51
	s_lshl_b32 s0, s31, 8
	s_add_u32 s0, s28, s0
	s_addc_u32 s1, s29, 0
	s_add_u32 s4, s0, 0x1400
	s_addc_u32 s5, s1, 0
	v_writelane_b32 v254, s4, 52
	s_add_u32 s0, s0, 0x2400
	s_addc_u32 s1, s1, 0
	v_writelane_b32 v254, s5, 53
	v_writelane_b32 v254, s0, 54
	s_nop 1
	v_writelane_b32 v254, s1, 55
	s_add_u32 s0, s42, 0xc3400
	s_addc_u32 s1, s43, 0
	v_writelane_b32 v254, s0, 56
	s_nop 1
	v_writelane_b32 v254, s1, 57
	s_add_u32 s0, s42, 0xc3500
	s_addc_u32 s1, s43, 0
	v_writelane_b32 v254, s0, 58
	s_ashr_i32 s35, s34, 31
	s_add_i32 s65, 0, 0x4000
	v_writelane_b32 v254, s1, 59
	s_lshl_b64 s[0:1], s[34:35], 12
	v_writelane_b32 v254, s0, 60
	s_add_i32 s74, 0, 0x23f98
	s_nop 0
	v_writelane_b32 v254, s1, 61
	s_lshl_b64 s[0:1], s[34:35], 6
	v_writelane_b32 v254, s0, 62
	s_nop 1
	v_writelane_b32 v254, s1, 63
	s_lshl_b64 s[0:1], s[34:35], 11
	v_writelane_b32 v255, s0, 0
	s_nop 1
	v_writelane_b32 v255, s1, 1
	s_lshl_b32 s0, s2, 7
	v_writelane_b32 v255, s0, 2
	s_lshl_b32 s0, s2, 6
	v_writelane_b32 v255, s0, 3
	s_add_i32 s0, 0, 0x23f90
	v_writelane_b32 v255, s0, 4
	s_add_i32 s0, 0, 0x300
	v_writelane_b32 v255, s0, 5
	s_add_i32 s0, 0, 0x23f88
	v_writelane_b32 v255, s0, 6
	s_add_i32 s0, 0, 0x23f80
	v_writelane_b32 v255, s0, 7
	s_add_i32 s0, 0, 0x23fc0
	v_writelane_b32 v255, s0, 8
	s_add_i32 s0, 0, 0x23fc4
	v_writelane_b32 v255, s0, 9
	v_writelane_b32 v255, s92, 10
	v_writelane_b32 v255, s34, 11
	s_nop 1
	v_writelane_b32 v255, s35, 12
	v_writelane_b32 v255, s62, 13
	v_writelane_b32 v255, s63, 14
	v_writelane_b32 v255, s65, 15
	v_writelane_b32 v255, s74, 16
	s_branch .LBB0_147

.LBB0_424:
	s_and_b64 vcc, exec, s[2:3]
	s_cbranch_vccz .LBB0_681
	s_add_i32 s7, s75, -2
	s_ashr_i32 s10, s7, 1
	s_cmp_eq_u32 s75, 1
	s_cbranch_scc1 .LBB0_488
	v_readlane_b32 s5, v255, 40
	s_bfe_u32 s4, s76, 0x10003
	s_nop 3
	s_xor_b32 s5, s5, 1
	s_and_b32 s4, s4, s5
	s_cmp_eq_u32 s75, 2
	s_cselect_b32 s5, 1, 0
	s_cmp_eq_u32 s75, 4
	s_cselect_b32 s6, 1, 0
	s_or_b32 s5, s5, s6
	s_and_b32 s4, s4, s5
	s_cmp_lg_u32 s4, 0
	s_cbranch_scc1 .LBB0_488
	s_bitcmp0_b32 s7, 1
	s_cselect_b64 s[2:3], -1, 0
	v_writelane_b32 v255, s96, 17
	s_and_b64 vcc, exec, s[2:3]
	s_nop 0
	v_writelane_b32 v255, s97, 18
	s_cbranch_vccnz .LBB0_428
	v_mov_b32_e32 v1, s74
	ds_read_b64 v[2:3], v1
	s_waitcnt lgkmcnt(0)
	v_readfirstlane_b32 s5, v3
	v_readfirstlane_b32 s4, v2
	s_nop 1
	v_writelane_b32 v255, s4, 17
	s_nop 1
	v_writelane_b32 v255, s5, 18

.LBB0_488:
	v_readlane_b32 s2, v255, 40
	s_nop 3
	s_cmp_eq_u32 s2, 1
	s_cbranch_scc1 .LBB0_681
	s_cmp_gt_i32 s10, 1
	s_cbranch_scc1 .LBB0_681
	s_and_b32 s2, s7, 2
	s_cmp_eq_u32 s2, 0
	s_cselect_b64 s[12:13], -1, 0
	s_cmp_lg_u32 s2, 0
	s_cbranch_scc1 .LBB0_491
	v_mov_b32_e32 v1, s74
	ds_read_b64 v[2:3], v1
	s_waitcnt lgkmcnt(0)
	v_readfirstlane_b32 s97, v3
	v_readfirstlane_b32 s96, v2

.LBB0_681:
	v_readlane_b32 s0, v254, 2
	s_add_i32 s16, s75, 1
	v_readlane_b32 s1, v254, 3
	v_readlane_b32 s40, v254, 6
	s_cmp_ge_i32 s16, s1
	s_mov_b64 s[0:1], -1
	v_readlane_b32 s42, v254, 8
	v_readlane_b32 s43, v254, 9
	v_readlane_b32 s34, v255, 11
	v_readlane_b32 s41, v254, 7
	v_readlane_b32 s35, v255, 12
	s_cbranch_scc1 .LBB0_146
	v_readlane_b32 s2, v255, 40
	v_readlane_b32 s3, v255, 10
	s_nop 3
	s_cmp_eq_u32 s2, 1
	s_cbranch_scc1 .Lsw_second_done
	s_bfe_u32 s3, s3, 0x10003
	s_cmp_eq_u32 s75, 2
	s_cselect_b32 s2, 1, 0
	s_cmp_eq_u32 s75, 4
	s_cselect_b32 s4, 1, 0
	s_or_b32 s2, s2, s4
	s_and_b32 s2, s2, s3
	s_cmp_lg_u32 s2, 0
	s_cbranch_scc0 .Lsw_normal
	s_mov_b32 s2, 1
	s_nop 0
	v_writelane_b32 v255, s2, 40
	s_mov_b32 s16, s75
	s_branch .LBB0_145
.Lsw_second_done:
	s_mov_b32 s2, 0
	s_nop 0
	v_writelane_b32 v255, s2, 40
.Lsw_normal:
	s_cmp_lt_i32 s75, 5
	s_cbranch_scc1 .LBB0_684
	s_cmp_lg_u32 s75, 5
	s_cselect_b64 s[0:1], -1, 0
	s_cbranch_execz .LBB0_685
	s_branch .LBB0_686
